# cache-policy lever on P6: the f32 h1 stores (consumed two phases later) marked sc0 sc1 like the P1 epilogue; bf16 h1b stores unchanged; code layout identical to previous best
# speedup vs baseline: 1.0040x; 1.0014x over previous
; __device__ __forceinline__ unsigned cvt_pk_bf16(float lo, float hi) { unsigned r; asm volatile("v_cvt_pk_bf16_f32 %0, %1, %2" : "=v"(r) : "v"(lo), "v"(hi)); return r; }
;     __device__ __forceinline__ void operator()(const f32x4 (&acc)[2][2][4][2], const Unit& u, int wr, int wc, int fr, int fq) const {
;     ...
;             for (int m = 0; m < 4; ++m) { const size_t row = (size_t)(row0 + ai * HALF + m * 16); float ss = 0.f;
; #pragma unroll
;                 for (int bj = 0; bj < 2; ++bj) { const int col = u.pn * BM + bj * HALF + wc * 32 + 8 * fq;
;                     const float* xp = x + row * 2048 + col; float* hp = h1 + row * 2048 + col;
;                     const f32x4 a0 = *(const f32x4*)xp + acc[ai][bj][m][0], a1 = *(const f32x4*)(xp + 4) + acc[ai][bj][m][1];
;                     *(f32x4*)hp = a0; *(f32x4*)(hp + 4) = a1;
;                     ss += a0[0] * a0[0] + a0[1] * a0[1] + a0[2] * a0[2] + a0[3] * a0[3] + a1[0] * a1[0] + a1[1] * a1[1] + a1[2] * a1[2] + a1[3] * a1[3];
;                     u32x4 w; w.x = cvt_pk_bf16(a0[0], a0[1]); w.y = cvt_pk_bf16(a0[2], a0[3]); w.z = cvt_pk_bf16(a1[0], a1[1]); w.w = cvt_pk_bf16(a1[2], a1[3]);
;                     *(u32x4*)(h1b + row * 2048 + col) = w; }
;                 ss += __shfl_xor(ss, 16); ss += __shfl_xor(ss, 32);
;                 if (fq == 0) atomicAdd(rowsq + row, ss); }
.LBB0_667:
	v_lshl_add_u32 v148, s30, 8, v150
	v_lshl_or_b32 v144, s40, 8, v152
	v_ashrrev_i32_e32 v149, 31, v148
	v_lshlrev_b64 v[166:167], 13, v[148:149]
	v_ashrrev_i32_e32 v145, 31, v144
	v_lshl_add_u64 v[158:159], s[36:37], 0, v[166:167]
	v_lshlrev_b64 v[146:147], 2, v[144:145]
	v_lshl_add_u64 v[168:169], v[158:159], 0, v[146:147]
	global_load_dwordx4 v[158:161], v[168:169], off
	global_load_dwordx4 v[162:165], v[168:169], off offset:16
	v_lshlrev_b64 v[170:171], 12, v[148:149]
	v_lshl_add_u64 v[166:167], s[26:27], 0, v[166:167]
	v_lshl_add_u64 v[170:171], s[10:11], 0, v[170:171]
	v_lshl_add_u64 v[172:173], v[166:167], 0, v[146:147]
	v_lshl_add_u64 v[170:171], v[144:145], 1, v[170:171]
	v_xor_b32_e32 v157, 32, v156
	s_waitcnt vmcnt(0)
	v_pk_add_f32 v[126:127], v[126:127], v[160:161]
	v_pk_add_f32 v[124:125], v[124:125], v[158:159]
	v_pk_add_f32 v[160:161], v[122:123], v[164:165]
	v_pk_add_f32 v[158:159], v[120:121], v[162:163]
	global_store_dwordx4 v[172:173], v[124:127], off sc0 sc1
	global_store_dwordx4 v[172:173], v[158:161], off offset:16 sc0 sc1
	v_cvt_pk_bf16_f32 v120, v124, v125
	v_cvt_pk_bf16_f32 v121, v126, v127
	v_cvt_pk_bf16_f32 v122, v158, v159
	v_cvt_pk_bf16_f32 v123, v160, v161
	global_store_dwordx4 v[170:171], v[120:123], off
	global_load_dwordx4 v[162:165], v[168:169], off offset:512
	s_nop 0
	global_load_dwordx4 v[166:169], v[168:169], off offset:528
	v_mul_f32_e32 v174, v125, v125
	v_fmac_f32_e32 v174, v124, v124
	v_fmac_f32_e32 v174, v126, v126
	v_fmac_f32_e32 v174, v127, v127
	v_and_b32_e32 v121, 64, v156
	v_fmac_f32_e32 v174, v158, v158
	v_xor_b32_e32 v120, 16, v156
	v_add_u32_e32 v121, 64, v121
	v_fmac_f32_e32 v174, v159, v159
	v_cmp_lt_i32_e32 vcc, v120, v121
	v_fmac_f32_e32 v174, v160, v160
	v_fmac_f32_e32 v174, v161, v161
	v_cndmask_b32_e32 v120, v156, v120, vcc
	v_lshlrev_b32_e32 v120, 2, v120
	v_cmp_lt_i32_e32 vcc, v157, v121
	s_waitcnt vmcnt(1)
	v_pk_add_f32 v[116:117], v[116:117], v[162:163]
	s_waitcnt vmcnt(0)
	v_pk_add_f32 v[122:123], v[112:113], v[166:167]
	v_mul_f32_e32 v112, v117, v117
	v_pk_add_f32 v[118:119], v[118:119], v[164:165]
	v_fmac_f32_e32 v112, v116, v116
	v_fmac_f32_e32 v112, v118, v118
	v_fmac_f32_e32 v112, v119, v119
	v_fmac_f32_e32 v112, v122, v122
	v_pk_add_f32 v[124:125], v[114:115], v[168:169]
	v_fmac_f32_e32 v112, v123, v123
	v_fmac_f32_e32 v112, v124, v124
	v_fmac_f32_e32 v112, v125, v125
	v_add_f32_e32 v112, v174, v112
	ds_bpermute_b32 v113, v120, v112
	v_cndmask_b32_e32 v114, v156, v157, vcc
	v_lshlrev_b32_e32 v114, 2, v114
	global_store_dwordx4 v[172:173], v[116:119], off offset:512 sc0 sc1
	global_store_dwordx4 v[172:173], v[122:125], off offset:528 sc0 sc1
	s_waitcnt lgkmcnt(0)
	v_add_f32_e32 v112, v112, v113
	ds_bpermute_b32 v113, v114, v112
	v_cvt_pk_bf16_f32 v116, v116, v117
	v_cvt_pk_bf16_f32 v117, v118, v119
	v_cvt_pk_bf16_f32 v118, v122, v123
	v_cvt_pk_bf16_f32 v119, v124, v125
	global_store_dwordx4 v[170:171], v[116:119], off offset:256
	s_and_saveexec_b64 s[30:31], s[0:1]
	s_cbranch_execz .LBB0_669
	v_lshl_add_u64 v[116:117], v[148:149], 2, s[12:13]
	s_waitcnt lgkmcnt(0)
	v_add_f32_e32 v112, v112, v113
	global_atomic_add_f32 v[116:117], v112, off
.LBB0_669:
	s_or_b64 exec, exec, s[30:31]
	v_or_b32_e32 v112, 16, v148
	s_waitcnt lgkmcnt(0)
	v_ashrrev_i32_e32 v113, 31, v112
	v_lshlrev_b64 v[126:127], 13, v[112:113]
	v_lshl_add_u64 v[116:117], s[36:37], 0, v[126:127]
	v_lshl_add_u64 v[158:159], v[116:117], 0, v[146:147]
	global_load_dwordx4 v[116:119], v[158:159], off
	global_load_dwordx4 v[122:125], v[158:159], off offset:16
	v_lshlrev_b64 v[160:161], 12, v[112:113]
	v_lshl_add_u64 v[126:127], s[26:27], 0, v[126:127]
	v_lshl_add_u64 v[160:161], s[10:11], 0, v[160:161]
	v_lshl_add_u64 v[126:127], v[126:127], 0, v[146:147]
	v_lshl_add_u64 v[160:161], v[144:145], 1, v[160:161]
	s_waitcnt vmcnt(1)
	v_pk_add_f32 v[110:111], v[110:111], v[118:119]
	v_pk_add_f32 v[108:109], v[108:109], v[116:117]
	s_waitcnt vmcnt(0)
	v_pk_add_f32 v[106:107], v[106:107], v[124:125]
	v_pk_add_f32 v[104:105], v[104:105], v[122:123]
	global_store_dwordx4 v[126:127], v[108:111], off sc0 sc1
	global_store_dwordx4 v[126:127], v[104:107], off offset:16 sc0 sc1
	v_cvt_pk_bf16_f32 v116, v108, v109
	v_cvt_pk_bf16_f32 v117, v110, v111
	v_cvt_pk_bf16_f32 v118, v104, v105
	v_cvt_pk_bf16_f32 v119, v106, v107
	global_store_dwordx4 v[160:161], v[116:119], off
	global_load_dwordx4 v[116:119], v[158:159], off offset:512
	s_nop 0
	global_load_dwordx4 v[122:125], v[158:159], off offset:528
	v_mul_f32_e32 v109, v109, v109
	v_fmac_f32_e32 v109, v108, v108
	v_fmac_f32_e32 v109, v110, v110
	v_fmac_f32_e32 v109, v111, v111
	v_fmac_f32_e32 v109, v104, v104
	v_fmac_f32_e32 v109, v105, v105
	v_fmac_f32_e32 v109, v106, v106
	v_fmac_f32_e32 v109, v107, v107
	s_waitcnt vmcnt(1)
	v_pk_add_f32 v[100:101], v[100:101], v[116:117]
	s_waitcnt vmcnt(0)
	v_pk_add_f32 v[104:105], v[96:97], v[122:123]
	v_mul_f32_e32 v96, v101, v101
	v_pk_add_f32 v[102:103], v[102:103], v[118:119]
	v_fmac_f32_e32 v96, v100, v100
	v_fmac_f32_e32 v96, v102, v102
	v_fmac_f32_e32 v96, v103, v103
	v_fmac_f32_e32 v96, v104, v104
	v_pk_add_f32 v[106:107], v[98:99], v[124:125]
	v_fmac_f32_e32 v96, v105, v105
	v_fmac_f32_e32 v96, v106, v106
	v_fmac_f32_e32 v96, v107, v107
	v_add_f32_e32 v96, v109, v96
	ds_bpermute_b32 v97, v120, v96
	global_store_dwordx4 v[126:127], v[100:103], off offset:512 sc0 sc1
	global_store_dwordx4 v[126:127], v[104:107], off offset:528 sc0 sc1
	v_cvt_pk_bf16_f32 v98, v100, v101
	v_cvt_pk_bf16_f32 v99, v102, v103
	s_waitcnt lgkmcnt(0)
	v_add_f32_e32 v96, v96, v97
	ds_bpermute_b32 v97, v114, v96
	v_cvt_pk_bf16_f32 v100, v104, v105
	v_cvt_pk_bf16_f32 v101, v106, v107
	global_store_dwordx4 v[160:161], v[98:101], off offset:256
	s_and_saveexec_b64 s[30:31], s[0:1]
	s_cbranch_execz .LBB0_671
	v_lshl_add_u64 v[98:99], v[112:113], 2, s[12:13]
	s_waitcnt lgkmcnt(0)
	v_add_f32_e32 v96, v96, v97
	global_atomic_add_f32 v[98:99], v96, off
; __device__ __forceinline__ unsigned cvt_pk_bf16(float lo, float hi) { unsigned r; asm volatile("v_cvt_pk_bf16_f32 %0, %1, %2" : "=v"(r) : "v"(lo), "v"(hi)); return r; }
;     __device__ __forceinline__ void operator()(const f32x4 (&acc)[2][2][4][2], const Unit& u, int wr, int wc, int fr, int fq) const {
;     ...
;             for (int m = 0; m < 4; ++m) { const size_t row = (size_t)(row0 + ai * HALF + m * 16); float ss = 0.f;
; #pragma unroll
;                 for (int bj = 0; bj < 2; ++bj) { const int col = u.pn * BM + bj * HALF + wc * 32 + 8 * fq;
;                     const float* xp = x + row * 2048 + col; float* hp = h1 + row * 2048 + col;
;                     const f32x4 a0 = *(const f32x4*)xp + acc[ai][bj][m][0], a1 = *(const f32x4*)(xp + 4) + acc[ai][bj][m][1];
;                     *(f32x4*)hp = a0; *(f32x4*)(hp + 4) = a1;
;                     ss += a0[0] * a0[0] + a0[1] * a0[1] + a0[2] * a0[2] + a0[3] * a0[3] + a1[0] * a1[0] + a1[1] * a1[1] + a1[2] * a1[2] + a1[3] * a1[3];
;                     u32x4 w; w.x = cvt_pk_bf16(a0[0], a0[1]); w.y = cvt_pk_bf16(a0[2], a0[3]); w.z = cvt_pk_bf16(a1[0], a1[1]); w.w = cvt_pk_bf16(a1[2], a1[3]);
;                     *(u32x4*)(h1b + row * 2048 + col) = w; }
;                 ss += __shfl_xor(ss, 16); ss += __shfl_xor(ss, 32);
;                 if (fq == 0) atomicAdd(rowsq + row, ss); }
.LBB0_671:
	s_or_b64 exec, exec, s[30:31]
	v_or_b32_e32 v96, 32, v148
	s_waitcnt lgkmcnt(0)
	v_ashrrev_i32_e32 v97, 31, v96
	v_lshlrev_b64 v[106:107], 13, v[96:97]
	v_lshl_add_u64 v[98:99], s[36:37], 0, v[106:107]
	v_lshl_add_u64 v[108:109], v[98:99], 0, v[146:147]
	global_load_dwordx4 v[98:101], v[108:109], off
	global_load_dwordx4 v[102:105], v[108:109], off offset:16
	v_lshlrev_b64 v[110:111], 12, v[96:97]
	v_lshl_add_u64 v[106:107], s[26:27], 0, v[106:107]
	v_lshl_add_u64 v[110:111], s[10:11], 0, v[110:111]
	v_lshl_add_u64 v[106:107], v[106:107], 0, v[146:147]
	v_lshl_add_u64 v[110:111], v[144:145], 1, v[110:111]
	s_waitcnt vmcnt(1)
	v_pk_add_f32 v[94:95], v[94:95], v[100:101]
	v_pk_add_f32 v[92:93], v[92:93], v[98:99]
	s_waitcnt vmcnt(0)
	v_pk_add_f32 v[90:91], v[90:91], v[104:105]
	v_pk_add_f32 v[88:89], v[88:89], v[102:103]
	global_store_dwordx4 v[106:107], v[92:95], off sc0 sc1
	global_store_dwordx4 v[106:107], v[88:91], off offset:16 sc0 sc1
	v_cvt_pk_bf16_f32 v98, v92, v93
	v_cvt_pk_bf16_f32 v99, v94, v95
	v_cvt_pk_bf16_f32 v100, v88, v89
	v_cvt_pk_bf16_f32 v101, v90, v91
	global_store_dwordx4 v[110:111], v[98:101], off
	global_load_dwordx4 v[98:101], v[108:109], off offset:512
	s_nop 0
	global_load_dwordx4 v[102:105], v[108:109], off offset:528
	v_mul_f32_e32 v93, v93, v93
	v_fmac_f32_e32 v93, v92, v92
	v_fmac_f32_e32 v93, v94, v94
	v_fmac_f32_e32 v93, v95, v95
	v_fmac_f32_e32 v93, v88, v88
	v_fmac_f32_e32 v93, v89, v89
	v_fmac_f32_e32 v93, v90, v90
	v_fmac_f32_e32 v93, v91, v91
	s_waitcnt vmcnt(1)
	v_pk_add_f32 v[84:85], v[84:85], v[98:99]
	s_waitcnt vmcnt(0)
	v_pk_add_f32 v[88:89], v[80:81], v[102:103]
	v_mul_f32_e32 v80, v85, v85
	v_pk_add_f32 v[86:87], v[86:87], v[100:101]
	v_fmac_f32_e32 v80, v84, v84
	v_fmac_f32_e32 v80, v86, v86
	v_fmac_f32_e32 v80, v87, v87
	v_fmac_f32_e32 v80, v88, v88
	v_pk_add_f32 v[90:91], v[82:83], v[104:105]
	v_fmac_f32_e32 v80, v89, v89
	v_fmac_f32_e32 v80, v90, v90
	v_fmac_f32_e32 v80, v91, v91
	v_add_f32_e32 v80, v93, v80
	ds_bpermute_b32 v81, v120, v80
	global_store_dwordx4 v[106:107], v[84:87], off offset:512 sc0 sc1
	global_store_dwordx4 v[106:107], v[88:91], off offset:528 sc0 sc1
	v_cvt_pk_bf16_f32 v82, v84, v85
	v_cvt_pk_bf16_f32 v83, v86, v87
	s_waitcnt lgkmcnt(0)
	v_add_f32_e32 v80, v80, v81
	ds_bpermute_b32 v81, v114, v80
	v_cvt_pk_bf16_f32 v84, v88, v89
	v_cvt_pk_bf16_f32 v85, v90, v91
	global_store_dwordx4 v[110:111], v[82:85], off offset:256
	s_and_saveexec_b64 s[30:31], s[0:1]
	s_cbranch_execz .LBB0_673
	v_lshl_add_u64 v[82:83], v[96:97], 2, s[12:13]
	s_waitcnt lgkmcnt(0)
	v_add_f32_e32 v80, v80, v81
	global_atomic_add_f32 v[82:83], v80, off
.LBB0_673:
	s_or_b64 exec, exec, s[30:31]
	v_or_b32_e32 v80, 48, v148
	s_waitcnt lgkmcnt(0)
	v_ashrrev_i32_e32 v81, 31, v80
	v_lshlrev_b64 v[90:91], 13, v[80:81]
	v_lshl_add_u64 v[82:83], s[36:37], 0, v[90:91]
	v_lshl_add_u64 v[92:93], v[82:83], 0, v[146:147]
	global_load_dwordx4 v[82:85], v[92:93], off
	global_load_dwordx4 v[86:89], v[92:93], off offset:16
	v_lshlrev_b64 v[94:95], 12, v[80:81]
	v_lshl_add_u64 v[90:91], s[26:27], 0, v[90:91]
	v_lshl_add_u64 v[94:95], s[10:11], 0, v[94:95]
	v_lshl_add_u64 v[90:91], v[90:91], 0, v[146:147]
	v_lshl_add_u64 v[94:95], v[144:145], 1, v[94:95]
	s_waitcnt vmcnt(1)
	v_pk_add_f32 v[78:79], v[78:79], v[84:85]
	v_pk_add_f32 v[76:77], v[76:77], v[82:83]
	s_waitcnt vmcnt(0)
	v_pk_add_f32 v[74:75], v[74:75], v[88:89]
	v_pk_add_f32 v[72:73], v[72:73], v[86:87]
	global_store_dwordx4 v[90:91], v[76:79], off sc0 sc1
	global_store_dwordx4 v[90:91], v[72:75], off offset:16 sc0 sc1
	v_cvt_pk_bf16_f32 v82, v76, v77
	v_cvt_pk_bf16_f32 v83, v78, v79
	v_cvt_pk_bf16_f32 v84, v72, v73
	v_cvt_pk_bf16_f32 v85, v74, v75
	global_store_dwordx4 v[94:95], v[82:85], off
	global_load_dwordx4 v[82:85], v[92:93], off offset:512
	s_nop 0
	global_load_dwordx4 v[86:89], v[92:93], off offset:528
	v_mul_f32_e32 v77, v77, v77
	v_fmac_f32_e32 v77, v76, v76
	v_fmac_f32_e32 v77, v78, v78
	v_fmac_f32_e32 v77, v79, v79
	v_fmac_f32_e32 v77, v72, v72
	v_fmac_f32_e32 v77, v73, v73
	v_fmac_f32_e32 v77, v74, v74
	v_fmac_f32_e32 v77, v75, v75
	s_waitcnt vmcnt(1)
	v_pk_add_f32 v[68:69], v[68:69], v[82:83]
	s_waitcnt vmcnt(0)
	v_pk_add_f32 v[72:73], v[64:65], v[86:87]
	v_mul_f32_e32 v64, v69, v69
	v_pk_add_f32 v[70:71], v[70:71], v[84:85]
	v_fmac_f32_e32 v64, v68, v68
	v_fmac_f32_e32 v64, v70, v70
	v_fmac_f32_e32 v64, v71, v71
	v_fmac_f32_e32 v64, v72, v72
	v_pk_add_f32 v[74:75], v[66:67], v[88:89]
	v_fmac_f32_e32 v64, v73, v73
	v_fmac_f32_e32 v64, v74, v74
	v_fmac_f32_e32 v64, v75, v75
	v_add_f32_e32 v64, v77, v64
	ds_bpermute_b32 v65, v120, v64
	global_store_dwordx4 v[90:91], v[68:71], off offset:512 sc0 sc1
	global_store_dwordx4 v[90:91], v[72:75], off offset:528 sc0 sc1
	v_cvt_pk_bf16_f32 v66, v68, v69
	v_cvt_pk_bf16_f32 v67, v70, v71
	s_waitcnt lgkmcnt(0)
	v_add_f32_e32 v64, v64, v65
	ds_bpermute_b32 v65, v114, v64
	v_cvt_pk_bf16_f32 v68, v72, v73
	v_cvt_pk_bf16_f32 v69, v74, v75
	global_store_dwordx4 v[94:95], v[66:69], off offset:256
	s_and_saveexec_b64 s[30:31], s[0:1]
	s_cbranch_execz .LBB0_675
	v_lshl_add_u64 v[66:67], v[80:81], 2, s[12:13]
	s_waitcnt lgkmcnt(0)
	v_add_f32_e32 v64, v64, v65
	global_atomic_add_f32 v[66:67], v64, off
; __device__ __forceinline__ unsigned cvt_pk_bf16(float lo, float hi) { unsigned r; asm volatile("v_cvt_pk_bf16_f32 %0, %1, %2" : "=v"(r) : "v"(lo), "v"(hi)); return r; }
;     __device__ __forceinline__ void operator()(const f32x4 (&acc)[2][2][4][2], const Unit& u, int wr, int wc, int fr, int fq) const {
;     ...
;             for (int m = 0; m < 4; ++m) { const size_t row = (size_t)(row0 + ai * HALF + m * 16); float ss = 0.f;
; #pragma unroll
;                 for (int bj = 0; bj < 2; ++bj) { const int col = u.pn * BM + bj * HALF + wc * 32 + 8 * fq;
;                     const float* xp = x + row * 2048 + col; float* hp = h1 + row * 2048 + col;
;                     const f32x4 a0 = *(const f32x4*)xp + acc[ai][bj][m][0], a1 = *(const f32x4*)(xp + 4) + acc[ai][bj][m][1];
;                     *(f32x4*)hp = a0; *(f32x4*)(hp + 4) = a1;
;                     ss += a0[0] * a0[0] + a0[1] * a0[1] + a0[2] * a0[2] + a0[3] * a0[3] + a1[0] * a1[0] + a1[1] * a1[1] + a1[2] * a1[2] + a1[3] * a1[3];
;                     u32x4 w; w.x = cvt_pk_bf16(a0[0], a0[1]); w.y = cvt_pk_bf16(a0[2], a0[3]); w.z = cvt_pk_bf16(a1[0], a1[1]); w.w = cvt_pk_bf16(a1[2], a1[3]);
;                     *(u32x4*)(h1b + row * 2048 + col) = w; }
;                 ss += __shfl_xor(ss, 16); ss += __shfl_xor(ss, 32);
;                 if (fq == 0) atomicAdd(rowsq + row, ss); }
.LBB0_675:
	s_or_b64 exec, exec, s[30:31]
	v_add_u32_e32 v64, 0x80, v148
	s_waitcnt lgkmcnt(0)
	v_ashrrev_i32_e32 v65, 31, v64
	v_lshlrev_b64 v[74:75], 13, v[64:65]
	v_lshl_add_u64 v[66:67], s[36:37], 0, v[74:75]
	v_lshl_add_u64 v[76:77], v[66:67], 0, v[146:147]
	global_load_dwordx4 v[66:69], v[76:77], off
	global_load_dwordx4 v[70:73], v[76:77], off offset:16
	v_lshlrev_b64 v[78:79], 12, v[64:65]
	v_lshl_add_u64 v[74:75], s[26:27], 0, v[74:75]
	v_lshl_add_u64 v[78:79], s[10:11], 0, v[78:79]
	v_lshl_add_u64 v[74:75], v[74:75], 0, v[146:147]
	v_lshl_add_u64 v[78:79], v[144:145], 1, v[78:79]
	s_waitcnt vmcnt(1)
	v_pk_add_f32 v[62:63], v[62:63], v[68:69]
	v_pk_add_f32 v[60:61], v[60:61], v[66:67]
	s_waitcnt vmcnt(0)
	v_pk_add_f32 v[58:59], v[58:59], v[72:73]
	v_pk_add_f32 v[56:57], v[56:57], v[70:71]
	global_store_dwordx4 v[74:75], v[60:63], off sc0 sc1
	global_store_dwordx4 v[74:75], v[56:59], off offset:16 sc0 sc1
	v_cvt_pk_bf16_f32 v66, v60, v61
	v_cvt_pk_bf16_f32 v67, v62, v63
	v_cvt_pk_bf16_f32 v68, v56, v57
	v_cvt_pk_bf16_f32 v69, v58, v59
	global_store_dwordx4 v[78:79], v[66:69], off
	global_load_dwordx4 v[66:69], v[76:77], off offset:512
	s_nop 0
	global_load_dwordx4 v[70:73], v[76:77], off offset:528
	v_mul_f32_e32 v61, v61, v61
	v_fmac_f32_e32 v61, v60, v60
	v_fmac_f32_e32 v61, v62, v62
	v_fmac_f32_e32 v61, v63, v63
	v_fmac_f32_e32 v61, v56, v56
	v_fmac_f32_e32 v61, v57, v57
	v_fmac_f32_e32 v61, v58, v58
	v_fmac_f32_e32 v61, v59, v59
	s_waitcnt vmcnt(1)
	v_pk_add_f32 v[52:53], v[52:53], v[66:67]
	s_waitcnt vmcnt(0)
	v_pk_add_f32 v[56:57], v[48:49], v[70:71]
	v_mul_f32_e32 v48, v53, v53
	v_pk_add_f32 v[54:55], v[54:55], v[68:69]
	v_fmac_f32_e32 v48, v52, v52
	v_fmac_f32_e32 v48, v54, v54
	v_fmac_f32_e32 v48, v55, v55
	v_fmac_f32_e32 v48, v56, v56
	v_pk_add_f32 v[58:59], v[50:51], v[72:73]
	v_fmac_f32_e32 v48, v57, v57
	v_fmac_f32_e32 v48, v58, v58
	v_fmac_f32_e32 v48, v59, v59
	v_add_f32_e32 v48, v61, v48
	ds_bpermute_b32 v49, v120, v48
	global_store_dwordx4 v[74:75], v[52:55], off offset:512 sc0 sc1
	global_store_dwordx4 v[74:75], v[56:59], off offset:528 sc0 sc1
	v_cvt_pk_bf16_f32 v50, v52, v53
	v_cvt_pk_bf16_f32 v51, v54, v55
	s_waitcnt lgkmcnt(0)
	v_add_f32_e32 v48, v48, v49
	ds_bpermute_b32 v49, v114, v48
	v_cvt_pk_bf16_f32 v52, v56, v57
	v_cvt_pk_bf16_f32 v53, v58, v59
	global_store_dwordx4 v[78:79], v[50:53], off offset:256
	s_and_saveexec_b64 s[30:31], s[0:1]
	s_cbranch_execz .LBB0_677
	v_lshl_add_u64 v[50:51], v[64:65], 2, s[12:13]
	s_waitcnt lgkmcnt(0)
	v_add_f32_e32 v48, v48, v49
	global_atomic_add_f32 v[50:51], v48, off
.LBB0_677:
	s_or_b64 exec, exec, s[30:31]
	v_add_u32_e32 v48, 0x90, v148
	s_waitcnt lgkmcnt(0)
	v_ashrrev_i32_e32 v49, 31, v48
	v_lshlrev_b64 v[58:59], 13, v[48:49]
	v_lshl_add_u64 v[50:51], s[36:37], 0, v[58:59]
	v_lshl_add_u64 v[60:61], v[50:51], 0, v[146:147]
	global_load_dwordx4 v[50:53], v[60:61], off
	global_load_dwordx4 v[54:57], v[60:61], off offset:16
	v_lshlrev_b64 v[62:63], 12, v[48:49]
	v_lshl_add_u64 v[58:59], s[26:27], 0, v[58:59]
	v_lshl_add_u64 v[62:63], s[10:11], 0, v[62:63]
	v_lshl_add_u64 v[58:59], v[58:59], 0, v[146:147]
	v_lshl_add_u64 v[62:63], v[144:145], 1, v[62:63]
	s_waitcnt vmcnt(1)
	v_pk_add_f32 v[46:47], v[46:47], v[52:53]
	v_pk_add_f32 v[44:45], v[44:45], v[50:51]
	s_waitcnt vmcnt(0)
	v_pk_add_f32 v[42:43], v[42:43], v[56:57]
	v_pk_add_f32 v[40:41], v[40:41], v[54:55]
	global_store_dwordx4 v[58:59], v[44:47], off sc0 sc1
	global_store_dwordx4 v[58:59], v[40:43], off offset:16 sc0 sc1
	v_cvt_pk_bf16_f32 v50, v44, v45
	v_cvt_pk_bf16_f32 v51, v46, v47
	v_cvt_pk_bf16_f32 v52, v40, v41
	v_cvt_pk_bf16_f32 v53, v42, v43
	global_store_dwordx4 v[62:63], v[50:53], off
	global_load_dwordx4 v[50:53], v[60:61], off offset:512
	s_nop 0
	global_load_dwordx4 v[54:57], v[60:61], off offset:528
	v_mul_f32_e32 v45, v45, v45
	v_fmac_f32_e32 v45, v44, v44
	v_fmac_f32_e32 v45, v46, v46
	v_fmac_f32_e32 v45, v47, v47
	v_fmac_f32_e32 v45, v40, v40
	v_fmac_f32_e32 v45, v41, v41
	v_fmac_f32_e32 v45, v42, v42
	v_fmac_f32_e32 v45, v43, v43
	s_waitcnt vmcnt(1)
	v_pk_add_f32 v[36:37], v[36:37], v[50:51]
	s_waitcnt vmcnt(0)
	v_pk_add_f32 v[40:41], v[32:33], v[54:55]
	v_mul_f32_e32 v32, v37, v37
	v_pk_add_f32 v[38:39], v[38:39], v[52:53]
	v_fmac_f32_e32 v32, v36, v36
	v_fmac_f32_e32 v32, v38, v38
	v_fmac_f32_e32 v32, v39, v39
	v_fmac_f32_e32 v32, v40, v40
	v_pk_add_f32 v[42:43], v[34:35], v[56:57]
	v_fmac_f32_e32 v32, v41, v41
	v_fmac_f32_e32 v32, v42, v42
	v_fmac_f32_e32 v32, v43, v43
	v_add_f32_e32 v32, v45, v32
	ds_bpermute_b32 v33, v120, v32
	global_store_dwordx4 v[58:59], v[36:39], off offset:512 sc0 sc1
	global_store_dwordx4 v[58:59], v[40:43], off offset:528 sc0 sc1
	v_cvt_pk_bf16_f32 v34, v36, v37
	v_cvt_pk_bf16_f32 v35, v38, v39
	s_waitcnt lgkmcnt(0)
	v_add_f32_e32 v32, v32, v33
	ds_bpermute_b32 v33, v114, v32
	v_cvt_pk_bf16_f32 v36, v40, v41
	v_cvt_pk_bf16_f32 v37, v42, v43
	global_store_dwordx4 v[62:63], v[34:37], off offset:256
	s_and_saveexec_b64 s[30:31], s[0:1]
	s_cbranch_execz .LBB0_679
	v_lshl_add_u64 v[34:35], v[48:49], 2, s[12:13]
	s_waitcnt lgkmcnt(0)
	v_add_f32_e32 v32, v32, v33
	global_atomic_add_f32 v[34:35], v32, off
; __device__ __forceinline__ unsigned cvt_pk_bf16(float lo, float hi) { unsigned r; asm volatile("v_cvt_pk_bf16_f32 %0, %1, %2" : "=v"(r) : "v"(lo), "v"(hi)); return r; }
;     __device__ __forceinline__ void operator()(const f32x4 (&acc)[2][2][4][2], const Unit& u, int wr, int wc, int fr, int fq) const {
;     ...
;             for (int m = 0; m < 4; ++m) { const size_t row = (size_t)(row0 + ai * HALF + m * 16); float ss = 0.f;
; #pragma unroll
;                 for (int bj = 0; bj < 2; ++bj) { const int col = u.pn * BM + bj * HALF + wc * 32 + 8 * fq;
;                     const float* xp = x + row * 2048 + col; float* hp = h1 + row * 2048 + col;
;                     const f32x4 a0 = *(const f32x4*)xp + acc[ai][bj][m][0], a1 = *(const f32x4*)(xp + 4) + acc[ai][bj][m][1];
;                     *(f32x4*)hp = a0; *(f32x4*)(hp + 4) = a1;
;                     ss += a0[0] * a0[0] + a0[1] * a0[1] + a0[2] * a0[2] + a0[3] * a0[3] + a1[0] * a1[0] + a1[1] * a1[1] + a1[2] * a1[2] + a1[3] * a1[3];
;                     u32x4 w; w.x = cvt_pk_bf16(a0[0], a0[1]); w.y = cvt_pk_bf16(a0[2], a0[3]); w.z = cvt_pk_bf16(a1[0], a1[1]); w.w = cvt_pk_bf16(a1[2], a1[3]);
;                     *(u32x4*)(h1b + row * 2048 + col) = w; }
;                 ss += __shfl_xor(ss, 16); ss += __shfl_xor(ss, 32);
;                 if (fq == 0) atomicAdd(rowsq + row, ss); }
.LBB0_679:
	s_or_b64 exec, exec, s[30:31]
	v_add_u32_e32 v32, 0xa0, v148
	s_waitcnt lgkmcnt(0)
	v_ashrrev_i32_e32 v33, 31, v32
	v_lshlrev_b64 v[42:43], 13, v[32:33]
	v_lshl_add_u64 v[34:35], s[36:37], 0, v[42:43]
	v_lshl_add_u64 v[44:45], v[34:35], 0, v[146:147]
	global_load_dwordx4 v[34:37], v[44:45], off
	global_load_dwordx4 v[38:41], v[44:45], off offset:16
	v_lshlrev_b64 v[46:47], 12, v[32:33]
	v_lshl_add_u64 v[42:43], s[26:27], 0, v[42:43]
	v_lshl_add_u64 v[46:47], s[10:11], 0, v[46:47]
	v_lshl_add_u64 v[42:43], v[42:43], 0, v[146:147]
	v_lshl_add_u64 v[46:47], v[144:145], 1, v[46:47]
	s_waitcnt vmcnt(1)
	v_pk_add_f32 v[30:31], v[30:31], v[36:37]
	v_pk_add_f32 v[28:29], v[28:29], v[34:35]
	s_waitcnt vmcnt(0)
	v_pk_add_f32 v[26:27], v[26:27], v[40:41]
	v_pk_add_f32 v[24:25], v[24:25], v[38:39]
	global_store_dwordx4 v[42:43], v[28:31], off sc0 sc1
	global_store_dwordx4 v[42:43], v[24:27], off offset:16 sc0 sc1
	v_cvt_pk_bf16_f32 v34, v28, v29
	v_cvt_pk_bf16_f32 v35, v30, v31
	v_cvt_pk_bf16_f32 v36, v24, v25
	v_cvt_pk_bf16_f32 v37, v26, v27
	global_store_dwordx4 v[46:47], v[34:37], off
	global_load_dwordx4 v[34:37], v[44:45], off offset:512
	s_nop 0
	global_load_dwordx4 v[38:41], v[44:45], off offset:528
	v_mul_f32_e32 v29, v29, v29
	v_fmac_f32_e32 v29, v28, v28
	v_fmac_f32_e32 v29, v30, v30
	v_fmac_f32_e32 v29, v31, v31
	v_fmac_f32_e32 v29, v24, v24
	v_fmac_f32_e32 v29, v25, v25
	v_fmac_f32_e32 v29, v26, v26
	v_fmac_f32_e32 v29, v27, v27
	s_waitcnt vmcnt(1)
	v_pk_add_f32 v[20:21], v[20:21], v[34:35]
	s_waitcnt vmcnt(0)
	v_pk_add_f32 v[24:25], v[16:17], v[38:39]
	v_mul_f32_e32 v16, v21, v21
	v_pk_add_f32 v[22:23], v[22:23], v[36:37]
	v_fmac_f32_e32 v16, v20, v20
	v_fmac_f32_e32 v16, v22, v22
	v_fmac_f32_e32 v16, v23, v23
	v_fmac_f32_e32 v16, v24, v24
	v_pk_add_f32 v[26:27], v[18:19], v[40:41]
	v_fmac_f32_e32 v16, v25, v25
	v_fmac_f32_e32 v16, v26, v26
	v_fmac_f32_e32 v16, v27, v27
	v_add_f32_e32 v16, v29, v16
	ds_bpermute_b32 v17, v120, v16
	global_store_dwordx4 v[42:43], v[20:23], off offset:512 sc0 sc1
	global_store_dwordx4 v[42:43], v[24:27], off offset:528 sc0 sc1
	v_cvt_pk_bf16_f32 v18, v20, v21
	v_cvt_pk_bf16_f32 v19, v22, v23
	s_waitcnt lgkmcnt(0)
	v_add_f32_e32 v16, v16, v17
	ds_bpermute_b32 v17, v114, v16
	v_cvt_pk_bf16_f32 v20, v24, v25
	v_cvt_pk_bf16_f32 v21, v26, v27
	global_store_dwordx4 v[46:47], v[18:21], off offset:256
	s_and_saveexec_b64 s[30:31], s[0:1]
	s_cbranch_execz .LBB0_681
	v_lshl_add_u64 v[18:19], v[32:33], 2, s[12:13]
	s_waitcnt lgkmcnt(0)
	v_add_f32_e32 v16, v16, v17
	global_atomic_add_f32 v[18:19], v16, off
.LBB0_681:
	s_or_b64 exec, exec, s[30:31]
	v_add_u32_e32 v16, 0xb0, v148
	s_waitcnt lgkmcnt(0)
	v_ashrrev_i32_e32 v17, 31, v16
	v_lshlrev_b64 v[26:27], 13, v[16:17]
	v_lshl_add_u64 v[18:19], s[36:37], 0, v[26:27]
	v_lshl_add_u64 v[28:29], v[18:19], 0, v[146:147]
	global_load_dwordx4 v[18:21], v[28:29], off
	global_load_dwordx4 v[22:25], v[28:29], off offset:16
	v_lshlrev_b64 v[30:31], 12, v[16:17]
	v_lshl_add_u64 v[26:27], s[26:27], 0, v[26:27]
	v_lshl_add_u64 v[30:31], s[10:11], 0, v[30:31]
	v_lshl_add_u64 v[26:27], v[26:27], 0, v[146:147]
	v_lshl_add_u64 v[30:31], v[144:145], 1, v[30:31]
	s_waitcnt vmcnt(1)
	v_pk_add_f32 v[14:15], v[14:15], v[20:21]
	v_pk_add_f32 v[12:13], v[12:13], v[18:19]
	s_waitcnt vmcnt(0)
	v_pk_add_f32 v[10:11], v[10:11], v[24:25]
	v_pk_add_f32 v[8:9], v[8:9], v[22:23]
	global_store_dwordx4 v[26:27], v[12:15], off sc0 sc1
	global_store_dwordx4 v[26:27], v[8:11], off offset:16 sc0 sc1
	v_cvt_pk_bf16_f32 v18, v12, v13
	v_cvt_pk_bf16_f32 v19, v14, v15
	v_cvt_pk_bf16_f32 v20, v8, v9
	v_cvt_pk_bf16_f32 v21, v10, v11
	global_store_dwordx4 v[30:31], v[18:21], off
	global_load_dwordx4 v[18:21], v[28:29], off offset:512
	s_nop 0
	global_load_dwordx4 v[22:25], v[28:29], off offset:528
	v_mul_f32_e32 v13, v13, v13
	v_fmac_f32_e32 v13, v12, v12
	v_fmac_f32_e32 v13, v14, v14
	v_fmac_f32_e32 v13, v15, v15
	v_fmac_f32_e32 v13, v8, v8
	v_fmac_f32_e32 v13, v9, v9
	v_fmac_f32_e32 v13, v10, v10
	v_fmac_f32_e32 v13, v11, v11
	s_waitcnt vmcnt(1)
	v_pk_add_f32 v[4:5], v[4:5], v[18:19]
	s_waitcnt vmcnt(0)
	v_pk_add_f32 v[8:9], v[0:1], v[22:23]
	v_mul_f32_e32 v0, v5, v5
	v_pk_add_f32 v[6:7], v[6:7], v[20:21]
	v_fmac_f32_e32 v0, v4, v4
	v_fmac_f32_e32 v0, v6, v6
	v_fmac_f32_e32 v0, v7, v7
	v_fmac_f32_e32 v0, v8, v8
	v_pk_add_f32 v[10:11], v[2:3], v[24:25]
	v_fmac_f32_e32 v0, v9, v9
	v_fmac_f32_e32 v0, v10, v10
	v_fmac_f32_e32 v0, v11, v11
	v_add_f32_e32 v0, v13, v0
	ds_bpermute_b32 v1, v120, v0
	global_store_dwordx4 v[26:27], v[4:7], off offset:512 sc0 sc1
	global_store_dwordx4 v[26:27], v[8:11], off offset:528 sc0 sc1
	v_cvt_pk_bf16_f32 v2, v4, v5
	v_cvt_pk_bf16_f32 v3, v6, v7
	s_waitcnt lgkmcnt(0)
	v_add_f32_e32 v0, v0, v1
	ds_bpermute_b32 v1, v114, v0
	v_cvt_pk_bf16_f32 v4, v8, v9
	v_cvt_pk_bf16_f32 v5, v10, v11
	global_store_dwordx4 v[30:31], v[2:5], off offset:256
	s_and_saveexec_b64 s[30:31], s[0:1]
	s_cbranch_execz .LBB0_683
	v_lshl_add_u64 v[2:3], v[16:17], 2, s[12:13]
	s_waitcnt lgkmcnt(0)
	v_add_f32_e32 v0, v0, v1
	global_atomic_add_f32 v[2:3], v0, off
